# v25 + dilated-attention QK phase: per k-step the two K fragments and the Q fragment (alternate buffer) are read together behind one wait, issued right after the previous step's MFMAs (8 LDS round trip
# speedup vs baseline: 1.0018x; 1.0018x over previous
.LBB0_228:
	s_cmp_eq_u32 s92, s84
	s_cselect_b64 s[16:17], -1, 0
	s_cmp_lg_u32 s92, s84
	s_cselect_b64 s[18:19], -1, 0
	s_lshl_b32 s5, s92, 6
	v_or_b32_e32 v0, s5, v179
	v_sub_u32_e32 v4, v153, v0
	v_cvt_f32_i32_e32 v0, v4
	v_cndmask_b32_e64 v1, v206, 0, s[16:17]
	s_mov_b32 s20, 2.0
	s_mov_b32 s22, 0x41200000
	v_fma_f32 v10, -v144, v0, -v1
	ds_read_b128 v[0:3], v180
	ds_read_b128 v[6:9], v176
	s_mov_b32 s24, 0x41800000
	s_mov_b32 s28, 0x41900000
	s_mov_b32 s21, 0x40400000
	s_mov_b32 s23, 0x41300000
	s_mov_b32 s25, 0x41880000
	s_mov_b32 s29, 0x41980000
	v_add_f32_e32 v14, v204, v10
	v_fma_f32 v96, 0, v144, v10
	v_add_f32_e32 v97, v144, v10
	v_pk_fma_f32 v[98:99], v[144:145], s[20:21], v[10:11] op_sel_hi:[1,1,0]
	v_pk_fma_f32 v[100:101], v[144:145], s[38:39], v[10:11] op_sel_hi:[1,1,0]
	v_pk_fma_f32 v[102:103], v[144:145], s[22:23], v[10:11] op_sel_hi:[1,1,0]
	v_pk_fma_f32 v[104:105], v[144:145], s[24:25], v[10:11] op_sel_hi:[1,1,0]
	v_pk_fma_f32 v[106:107], v[144:145], s[28:29], v[10:11] op_sel_hi:[1,1,0]
	v_pk_fma_f32 v[108:109], v[144:145], s[26:27], v[10:11] op_sel_hi:[1,1,0]
	v_pk_fma_f32 v[110:111], v[144:145], s[36:37], v[10:11] op_sel_hi:[1,1,0]
	ds_read_b128 v[10:13], v180 offset:8704
	v_fma_f32 v80, 0, v144, v14
	s_waitcnt lgkmcnt(1)
	v_mfma_f32_32x32x16_bf16 v[96:111], v[0:3], v[6:9], v[96:111]
	v_add_f32_e32 v81, v144, v14
	v_fma_f32 v82, v144, s20, v14
	v_fma_f32 v83, v145, s21, v14
	v_fma_f32 v84, v144, s38, v14
	v_fma_f32 v85, v145, s39, v14
	v_pk_fma_f32 v[86:87], v[144:145], s[22:23], v[14:15] op_sel_hi:[1,1,0]
	v_pk_fma_f32 v[88:89], v[144:145], s[24:25], v[14:15] op_sel_hi:[1,1,0]
	v_pk_fma_f32 v[90:91], v[144:145], s[28:29], v[14:15] op_sel_hi:[1,1,0]
	v_pk_fma_f32 v[92:93], v[144:145], s[26:27], v[14:15] op_sel_hi:[1,1,0]
	v_pk_fma_f32 v[94:95], v[144:145], s[36:37], v[14:15] op_sel_hi:[1,1,0]
	s_or_b32 s4, s5, 63
	s_sub_i32 s20, s49, s4
	s_waitcnt lgkmcnt(0)
	v_mfma_f32_32x32x16_bf16 v[80:95], v[10:13], v[6:9], v[80:95]
	ds_read_b128 v[0:3], v180 offset:32
	ds_read_b128 v[10:13], v180 offset:8736
	ds_read_b128 v[246:249], v176 offset:32
	s_mov_b32 s4, 0
	s_cmpk_gt_i32 s20, 0x200
	s_waitcnt lgkmcnt(0)
	v_mfma_f32_32x32x16_bf16 v[96:111], v[0:3], v[246:249], v[96:111]
	v_mfma_f32_32x32x16_bf16 v[80:95], v[10:13], v[246:249], v[80:95]
	ds_read_b128 v[0:3], v180 offset:64
	ds_read_b128 v[10:13], v180 offset:8768
	ds_read_b128 v[6:9], v176 offset:64
	s_waitcnt lgkmcnt(0)
	v_mfma_f32_32x32x16_bf16 v[96:111], v[0:3], v[6:9], v[96:111]
	v_mfma_f32_32x32x16_bf16 v[80:95], v[10:13], v[6:9], v[80:95]
	ds_read_b128 v[0:3], v180 offset:96
	ds_read_b128 v[10:13], v180 offset:8800
	ds_read_b128 v[246:249], v176 offset:96
	s_waitcnt lgkmcnt(0)
	v_mfma_f32_32x32x16_bf16 v[96:111], v[0:3], v[246:249], v[96:111]
	v_mfma_f32_32x32x16_bf16 v[80:95], v[10:13], v[246:249], v[80:95]
	ds_read_b128 v[0:3], v180 offset:128
	ds_read_b128 v[10:13], v180 offset:8832
	ds_read_b128 v[6:9], v176 offset:128
	s_waitcnt lgkmcnt(0)
	v_mfma_f32_32x32x16_bf16 v[96:111], v[0:3], v[6:9], v[96:111]
	v_mfma_f32_32x32x16_bf16 v[80:95], v[10:13], v[6:9], v[80:95]
	ds_read_b128 v[0:3], v180 offset:160
	ds_read_b128 v[10:13], v180 offset:8864
	ds_read_b128 v[246:249], v176 offset:160
	s_waitcnt lgkmcnt(0)
	v_mfma_f32_32x32x16_bf16 v[96:111], v[0:3], v[246:249], v[96:111]
	v_mfma_f32_32x32x16_bf16 v[80:95], v[10:13], v[246:249], v[80:95]
	ds_read_b128 v[0:3], v180 offset:192
	ds_read_b128 v[10:13], v180 offset:8896
	ds_read_b128 v[6:9], v176 offset:192
	s_waitcnt lgkmcnt(0)
	v_mfma_f32_32x32x16_bf16 v[96:111], v[0:3], v[6:9], v[96:111]
	v_mfma_f32_32x32x16_bf16 v[80:95], v[10:13], v[6:9], v[80:95]
	ds_read_b128 v[0:3], v180 offset:224
	ds_read_b128 v[10:13], v180 offset:8928
	ds_read_b128 v[246:249], v176 offset:224
	s_waitcnt lgkmcnt(0)
	v_mfma_f32_32x32x16_bf16 v[96:111], v[0:3], v[246:249], v[96:111]
	v_mfma_f32_32x32x16_bf16 v[80:95], v[10:13], v[246:249], v[80:95]
	s_nop 1
	s_cbranch_scc1 .LBB0_230
	s_sub_i32 s24, s46, s5
	s_cmpk_gt_i32 s20, 0x80
	s_cselect_b64 s[4:5], -1, 0
	s_cmpk_lt_i32 s24, 0x201
	s_cselect_b64 s[22:23], -1, 0
	s_and_b64 s[4:5], s[4:5], s[22:23]
	s_cmp_gt_i32 s20, -1
	s_cselect_b64 s[20:21], -1, 0
	s_cmpk_lt_i32 s24, 0x81
	s_cselect_b64 s[22:23], -1, 0
	s_and_b64 s[20:21], s[20:21], s[22:23]
	s_and_b64 s[20:21], s[20:21], exec
	s_cselect_b32 s20, 2, 3
	s_and_b64 s[4:5], s[4:5], exec
	s_cselect_b32 s4, 1, s20

.LBB0_429:
	s_cmp_eq_u32 s4, s84
	s_cselect_b64 s[16:17], -1, 0
	s_cmp_lg_u32 s4, s84
	s_cselect_b64 s[18:19], -1, 0
	s_lshl_b32 s5, s4, 6
	v_or_b32_e32 v0, s5, v179
	v_sub_u32_e32 v4, v153, v0
	v_cvt_f32_i32_e32 v0, v4
	v_cndmask_b32_e64 v1, v206, 0, s[16:17]
	s_mov_b32 s20, 2.0
	s_mov_b32 s22, 0x41200000
	v_fma_f32 v10, -v144, v0, -v1
	ds_read_b128 v[0:3], v180 offset:17408
	ds_read_b128 v[6:9], v176
	s_mov_b32 s24, 0x41800000
	s_mov_b32 s28, 0x41900000
	s_mov_b32 s21, 0x40400000
	s_mov_b32 s23, 0x41300000
	s_mov_b32 s25, 0x41880000
	s_mov_b32 s29, 0x41980000
	v_add_f32_e32 v14, v204, v10
	v_fma_f32 v96, 0, v144, v10
	v_add_f32_e32 v97, v144, v10
	v_pk_fma_f32 v[98:99], v[144:145], s[20:21], v[10:11] op_sel_hi:[1,1,0]
	v_pk_fma_f32 v[100:101], v[144:145], s[38:39], v[10:11] op_sel_hi:[1,1,0]
	v_pk_fma_f32 v[102:103], v[144:145], s[22:23], v[10:11] op_sel_hi:[1,1,0]
	v_pk_fma_f32 v[104:105], v[144:145], s[24:25], v[10:11] op_sel_hi:[1,1,0]
	v_pk_fma_f32 v[106:107], v[144:145], s[28:29], v[10:11] op_sel_hi:[1,1,0]
	v_pk_fma_f32 v[108:109], v[144:145], s[26:27], v[10:11] op_sel_hi:[1,1,0]
	v_pk_fma_f32 v[110:111], v[144:145], s[36:37], v[10:11] op_sel_hi:[1,1,0]
	ds_read_b128 v[10:13], v180 offset:26112
	v_fma_f32 v80, 0, v144, v14
	s_waitcnt lgkmcnt(1)
	v_mfma_f32_32x32x16_bf16 v[96:111], v[0:3], v[6:9], v[96:111]
	v_add_f32_e32 v81, v144, v14
	v_fma_f32 v82, v144, s20, v14
	v_fma_f32 v83, v145, s21, v14
	v_fma_f32 v84, v144, s38, v14
	v_fma_f32 v85, v145, s39, v14
	v_pk_fma_f32 v[86:87], v[144:145], s[22:23], v[14:15] op_sel_hi:[1,1,0]
	v_pk_fma_f32 v[88:89], v[144:145], s[24:25], v[14:15] op_sel_hi:[1,1,0]
	v_pk_fma_f32 v[90:91], v[144:145], s[28:29], v[14:15] op_sel_hi:[1,1,0]
	v_pk_fma_f32 v[92:93], v[144:145], s[26:27], v[14:15] op_sel_hi:[1,1,0]
	v_pk_fma_f32 v[94:95], v[144:145], s[36:37], v[14:15] op_sel_hi:[1,1,0]
	s_or_b32 s4, s5, 63
	s_sub_i32 s20, s49, s4
	s_waitcnt lgkmcnt(0)
	v_mfma_f32_32x32x16_bf16 v[80:95], v[10:13], v[6:9], v[80:95]
	ds_read_b128 v[0:3], v180 offset:17440
	ds_read_b128 v[10:13], v180 offset:26144
	ds_read_b128 v[246:249], v176 offset:32
	s_mov_b32 s4, 0
	s_cmpk_gt_i32 s20, 0x200
	s_waitcnt lgkmcnt(0)
	v_mfma_f32_32x32x16_bf16 v[96:111], v[0:3], v[246:249], v[96:111]
	v_mfma_f32_32x32x16_bf16 v[80:95], v[10:13], v[246:249], v[80:95]
	ds_read_b128 v[0:3], v180 offset:17472
	ds_read_b128 v[10:13], v180 offset:26176
	ds_read_b128 v[6:9], v176 offset:64
	s_waitcnt lgkmcnt(0)
	v_mfma_f32_32x32x16_bf16 v[96:111], v[0:3], v[6:9], v[96:111]
	v_mfma_f32_32x32x16_bf16 v[80:95], v[10:13], v[6:9], v[80:95]
	ds_read_b128 v[0:3], v180 offset:17504
	ds_read_b128 v[10:13], v180 offset:26208
	ds_read_b128 v[246:249], v176 offset:96
	s_waitcnt lgkmcnt(0)
	v_mfma_f32_32x32x16_bf16 v[96:111], v[0:3], v[246:249], v[96:111]
	v_mfma_f32_32x32x16_bf16 v[80:95], v[10:13], v[246:249], v[80:95]
	ds_read_b128 v[0:3], v180 offset:17536
	ds_read_b128 v[10:13], v180 offset:26240
	ds_read_b128 v[6:9], v176 offset:128
	s_waitcnt lgkmcnt(0)
	v_mfma_f32_32x32x16_bf16 v[96:111], v[0:3], v[6:9], v[96:111]
	v_mfma_f32_32x32x16_bf16 v[80:95], v[10:13], v[6:9], v[80:95]
	ds_read_b128 v[0:3], v180 offset:17568
	ds_read_b128 v[10:13], v180 offset:26272
	ds_read_b128 v[246:249], v176 offset:160
	s_waitcnt lgkmcnt(0)
	v_mfma_f32_32x32x16_bf16 v[96:111], v[0:3], v[246:249], v[96:111]
	v_mfma_f32_32x32x16_bf16 v[80:95], v[10:13], v[246:249], v[80:95]
	ds_read_b128 v[0:3], v180 offset:17600
	ds_read_b128 v[10:13], v180 offset:26304
	ds_read_b128 v[6:9], v176 offset:192
	s_waitcnt lgkmcnt(0)
	v_mfma_f32_32x32x16_bf16 v[96:111], v[0:3], v[6:9], v[96:111]
	v_mfma_f32_32x32x16_bf16 v[80:95], v[10:13], v[6:9], v[80:95]
	ds_read_b128 v[0:3], v180 offset:17632
	ds_read_b128 v[10:13], v180 offset:26336
	ds_read_b128 v[246:249], v176 offset:224
	s_waitcnt lgkmcnt(0)
	v_mfma_f32_32x32x16_bf16 v[96:111], v[0:3], v[246:249], v[96:111]
	v_mfma_f32_32x32x16_bf16 v[80:95], v[10:13], v[246:249], v[80:95]
	s_nop 1
	s_cbranch_scc1 .LBB0_431
	s_sub_i32 s24, s46, s5
	s_cmpk_gt_i32 s20, 0x80
	s_cselect_b64 s[4:5], -1, 0
	s_cmpk_lt_i32 s24, 0x201
	s_cselect_b64 s[22:23], -1, 0
	s_and_b64 s[4:5], s[4:5], s[22:23]
	s_cmp_gt_i32 s20, -1
	s_cselect_b64 s[20:21], -1, 0
	s_cmpk_lt_i32 s24, 0x81
	s_cselect_b64 s[22:23], -1, 0
	s_and_b64 s[20:21], s[20:21], s[22:23]
	s_and_b64 s[20:21], s[20:21], exec
	s_cselect_b32 s20, 2, 3
	s_and_b64 s[4:5], s[4:5], exec
	s_cselect_b32 s4, 1, s20

.LBB0_771:
	s_cmp_eq_u32 s92, s84
	s_cselect_b64 s[16:17], -1, 0
	s_cmp_lg_u32 s92, s84
	s_cselect_b64 s[18:19], -1, 0
	s_lshl_b32 s5, s92, 6
	v_or_b32_e32 v0, s5, v179
	v_sub_u32_e32 v4, v153, v0
	v_cvt_f32_i32_e32 v0, v4
	v_cndmask_b32_e64 v1, v206, 0, s[16:17]
	v_add_u32_e32 v15, s46, v180
	s_mov_b32 s20, 2.0
	v_fma_f32 v10, -v144, v0, -v1
	ds_read_b128 v[0:3], v15
	s_mov_b32 s22, 0x41200000
	s_mov_b32 s24, 0x41800000
	s_mov_b32 s28, 0x41900000
	s_mov_b32 s21, 0x40400000
	s_mov_b32 s23, 0x41300000
	s_mov_b32 s25, 0x41880000
	s_mov_b32 s29, 0x41980000
	v_add_f32_e32 v14, v204, v10
	v_fma_f32 v96, 0, v144, v10
	v_add_f32_e32 v97, v144, v10
	v_pk_fma_f32 v[98:99], v[144:145], s[20:21], v[10:11] op_sel_hi:[1,1,0]
	v_pk_fma_f32 v[100:101], v[144:145], s[38:39], v[10:11] op_sel_hi:[1,1,0]
	v_pk_fma_f32 v[102:103], v[144:145], s[22:23], v[10:11] op_sel_hi:[1,1,0]
	v_pk_fma_f32 v[104:105], v[144:145], s[24:25], v[10:11] op_sel_hi:[1,1,0]
	v_pk_fma_f32 v[106:107], v[144:145], s[28:29], v[10:11] op_sel_hi:[1,1,0]
	v_pk_fma_f32 v[108:109], v[144:145], s[26:27], v[10:11] op_sel_hi:[1,1,0]
	v_pk_fma_f32 v[110:111], v[144:145], s[36:37], v[10:11] op_sel_hi:[1,1,0]
	ds_read_b128 v[10:13], v15 offset:8704
	ds_read_b128 v[6:9], v176
	s_waitcnt lgkmcnt(0)
	v_mfma_f32_32x32x16_bf16 v[96:111], v[0:3], v[6:9], v[96:111]
	v_fma_f32 v80, 0, v144, v14
	v_add_f32_e32 v81, v144, v14
	v_fma_f32 v82, v144, s20, v14
	v_fma_f32 v83, v145, s21, v14
	v_fma_f32 v84, v144, s38, v14
	v_fma_f32 v85, v145, s39, v14
	v_pk_fma_f32 v[86:87], v[144:145], s[22:23], v[14:15] op_sel_hi:[1,1,0]
	v_pk_fma_f32 v[88:89], v[144:145], s[24:25], v[14:15] op_sel_hi:[1,1,0]
	v_pk_fma_f32 v[90:91], v[144:145], s[28:29], v[14:15] op_sel_hi:[1,1,0]
	v_pk_fma_f32 v[92:93], v[144:145], s[26:27], v[14:15] op_sel_hi:[1,1,0]
	v_pk_fma_f32 v[94:95], v[144:145], s[36:37], v[14:15] op_sel_hi:[1,1,0]
	s_or_b32 s4, s5, 63
	s_sub_i32 s20, s49, s4
	v_mfma_f32_32x32x16_bf16 v[80:95], v[10:13], v[6:9], v[80:95]
	ds_read_b128 v[0:3], v15 offset:32
	ds_read_b128 v[10:13], v15 offset:8736
	ds_read_b128 v[246:249], v176 offset:32
	s_mov_b32 s4, 0
	s_cmpk_gt_i32 s20, 0x200
	s_waitcnt lgkmcnt(0)
	v_mfma_f32_32x32x16_bf16 v[96:111], v[0:3], v[246:249], v[96:111]
	v_mfma_f32_32x32x16_bf16 v[80:95], v[10:13], v[246:249], v[80:95]
	ds_read_b128 v[0:3], v15 offset:64
	ds_read_b128 v[10:13], v15 offset:8768
	ds_read_b128 v[6:9], v176 offset:64
	s_waitcnt lgkmcnt(0)
	v_mfma_f32_32x32x16_bf16 v[96:111], v[0:3], v[6:9], v[96:111]
	v_mfma_f32_32x32x16_bf16 v[80:95], v[10:13], v[6:9], v[80:95]
	ds_read_b128 v[0:3], v15 offset:96
	ds_read_b128 v[10:13], v15 offset:8800
	ds_read_b128 v[246:249], v176 offset:96
	s_waitcnt lgkmcnt(0)
	v_mfma_f32_32x32x16_bf16 v[96:111], v[0:3], v[246:249], v[96:111]
	v_mfma_f32_32x32x16_bf16 v[80:95], v[10:13], v[246:249], v[80:95]
	ds_read_b128 v[0:3], v15 offset:128
	ds_read_b128 v[10:13], v15 offset:8832
	ds_read_b128 v[6:9], v176 offset:128
	s_waitcnt lgkmcnt(0)
	v_mfma_f32_32x32x16_bf16 v[96:111], v[0:3], v[6:9], v[96:111]
	v_mfma_f32_32x32x16_bf16 v[80:95], v[10:13], v[6:9], v[80:95]
	ds_read_b128 v[0:3], v15 offset:160
	ds_read_b128 v[10:13], v15 offset:8864
	ds_read_b128 v[246:249], v176 offset:160
	s_waitcnt lgkmcnt(0)
	v_mfma_f32_32x32x16_bf16 v[96:111], v[0:3], v[246:249], v[96:111]
	v_mfma_f32_32x32x16_bf16 v[80:95], v[10:13], v[246:249], v[80:95]
	ds_read_b128 v[0:3], v15 offset:192
	ds_read_b128 v[10:13], v15 offset:8896
	ds_read_b128 v[6:9], v176 offset:192
	s_waitcnt lgkmcnt(0)
	v_mfma_f32_32x32x16_bf16 v[96:111], v[0:3], v[6:9], v[96:111]
	v_mfma_f32_32x32x16_bf16 v[80:95], v[10:13], v[6:9], v[80:95]
	ds_read_b128 v[0:3], v15 offset:224
	ds_read_b128 v[10:13], v15 offset:8928
	ds_read_b128 v[246:249], v176 offset:224
	s_waitcnt lgkmcnt(0)
	v_mfma_f32_32x32x16_bf16 v[96:111], v[0:3], v[246:249], v[96:111]
	v_mfma_f32_32x32x16_bf16 v[80:95], v[10:13], v[246:249], v[80:95]
	s_nop 1
	s_cbranch_scc1 .LBB0_773
	s_sub_i32 s24, s93, s5
	s_cmpk_gt_i32 s20, 0x80
	s_cselect_b64 s[4:5], -1, 0
	s_cmpk_lt_i32 s24, 0x201
	s_cselect_b64 s[22:23], -1, 0
	s_and_b64 s[4:5], s[4:5], s[22:23]
	s_cmp_gt_i32 s20, -1
	s_cselect_b64 s[20:21], -1, 0
	s_cmpk_lt_i32 s24, 0x81
	s_cselect_b64 s[22:23], -1, 0
	s_and_b64 s[20:21], s[20:21], s[22:23]
	s_and_b64 s[20:21], s[20:21], exec
	s_cselect_b32 s20, 2, 3
	s_and_b64 s[4:5], s[4:5], exec
	s_cselect_b32 s4, 1, s20

.LBB0_972:
	s_cmp_eq_u32 s4, s84
	s_cselect_b64 s[16:17], -1, 0
	s_cmp_lg_u32 s4, s84
	s_cselect_b64 s[18:19], -1, 0
	s_lshl_b32 s5, s4, 6
	v_or_b32_e32 v0, s5, v179
	v_sub_u32_e32 v4, v153, v0
	v_cvt_f32_i32_e32 v0, v4
	v_cndmask_b32_e64 v1, v206, 0, s[16:17]
	v_add_u32_e32 v15, s44, v180
	s_mov_b32 s20, 2.0
	v_fma_f32 v10, -v144, v0, -v1
	ds_read_b128 v[0:3], v15
	s_mov_b32 s22, 0x41200000
	s_mov_b32 s24, 0x41800000
	s_mov_b32 s28, 0x41900000
	s_mov_b32 s21, 0x40400000
	s_mov_b32 s23, 0x41300000
	s_mov_b32 s25, 0x41880000
	s_mov_b32 s29, 0x41980000
	v_add_f32_e32 v14, v204, v10
	v_fma_f32 v96, 0, v144, v10
	v_add_f32_e32 v97, v144, v10
	v_pk_fma_f32 v[98:99], v[144:145], s[20:21], v[10:11] op_sel_hi:[1,1,0]
	v_pk_fma_f32 v[100:101], v[144:145], s[38:39], v[10:11] op_sel_hi:[1,1,0]
	v_pk_fma_f32 v[102:103], v[144:145], s[22:23], v[10:11] op_sel_hi:[1,1,0]
	v_pk_fma_f32 v[104:105], v[144:145], s[24:25], v[10:11] op_sel_hi:[1,1,0]
	v_pk_fma_f32 v[106:107], v[144:145], s[28:29], v[10:11] op_sel_hi:[1,1,0]
	v_pk_fma_f32 v[108:109], v[144:145], s[26:27], v[10:11] op_sel_hi:[1,1,0]
	v_pk_fma_f32 v[110:111], v[144:145], s[36:37], v[10:11] op_sel_hi:[1,1,0]
	ds_read_b128 v[10:13], v15 offset:8704
	ds_read_b128 v[6:9], v176
	s_waitcnt lgkmcnt(0)
	v_mfma_f32_32x32x16_bf16 v[96:111], v[0:3], v[6:9], v[96:111]
	v_fma_f32 v80, 0, v144, v14
	v_add_f32_e32 v81, v144, v14
	v_fma_f32 v82, v144, s20, v14
	v_fma_f32 v83, v145, s21, v14
	v_fma_f32 v84, v144, s38, v14
	v_fma_f32 v85, v145, s39, v14
	v_pk_fma_f32 v[86:87], v[144:145], s[22:23], v[14:15] op_sel_hi:[1,1,0]
	v_pk_fma_f32 v[88:89], v[144:145], s[24:25], v[14:15] op_sel_hi:[1,1,0]
	v_pk_fma_f32 v[90:91], v[144:145], s[28:29], v[14:15] op_sel_hi:[1,1,0]
	v_pk_fma_f32 v[92:93], v[144:145], s[26:27], v[14:15] op_sel_hi:[1,1,0]
	v_pk_fma_f32 v[94:95], v[144:145], s[36:37], v[14:15] op_sel_hi:[1,1,0]
	s_or_b32 s4, s5, 63
	s_sub_i32 s20, s49, s4
	v_mfma_f32_32x32x16_bf16 v[80:95], v[10:13], v[6:9], v[80:95]
	ds_read_b128 v[0:3], v15 offset:32
	ds_read_b128 v[10:13], v15 offset:8736
	ds_read_b128 v[246:249], v176 offset:32
	s_mov_b32 s4, 0
	s_cmpk_gt_i32 s20, 0x200
	s_waitcnt lgkmcnt(0)
	v_mfma_f32_32x32x16_bf16 v[96:111], v[0:3], v[246:249], v[96:111]
	v_mfma_f32_32x32x16_bf16 v[80:95], v[10:13], v[246:249], v[80:95]
	ds_read_b128 v[0:3], v15 offset:64
	ds_read_b128 v[10:13], v15 offset:8768
	ds_read_b128 v[6:9], v176 offset:64
	s_waitcnt lgkmcnt(0)
	v_mfma_f32_32x32x16_bf16 v[96:111], v[0:3], v[6:9], v[96:111]
	v_mfma_f32_32x32x16_bf16 v[80:95], v[10:13], v[6:9], v[80:95]
	ds_read_b128 v[0:3], v15 offset:96
	ds_read_b128 v[10:13], v15 offset:8800
	ds_read_b128 v[246:249], v176 offset:96
	s_waitcnt lgkmcnt(0)
	v_mfma_f32_32x32x16_bf16 v[96:111], v[0:3], v[246:249], v[96:111]
	v_mfma_f32_32x32x16_bf16 v[80:95], v[10:13], v[246:249], v[80:95]
	ds_read_b128 v[0:3], v15 offset:128
	ds_read_b128 v[10:13], v15 offset:8832
	ds_read_b128 v[6:9], v176 offset:128
	s_waitcnt lgkmcnt(0)
	v_mfma_f32_32x32x16_bf16 v[96:111], v[0:3], v[6:9], v[96:111]
	v_mfma_f32_32x32x16_bf16 v[80:95], v[10:13], v[6:9], v[80:95]
	ds_read_b128 v[0:3], v15 offset:160
	ds_read_b128 v[10:13], v15 offset:8864
	ds_read_b128 v[246:249], v176 offset:160
	s_waitcnt lgkmcnt(0)
	v_mfma_f32_32x32x16_bf16 v[96:111], v[0:3], v[246:249], v[96:111]
	v_mfma_f32_32x32x16_bf16 v[80:95], v[10:13], v[246:249], v[80:95]
	ds_read_b128 v[0:3], v15 offset:192
	ds_read_b128 v[10:13], v15 offset:8896
	ds_read_b128 v[6:9], v176 offset:192
	s_waitcnt lgkmcnt(0)
	v_mfma_f32_32x32x16_bf16 v[96:111], v[0:3], v[6:9], v[96:111]
	v_mfma_f32_32x32x16_bf16 v[80:95], v[10:13], v[6:9], v[80:95]
	ds_read_b128 v[0:3], v15 offset:224
	ds_read_b128 v[10:13], v15 offset:8928
	ds_read_b128 v[246:249], v176 offset:224
	s_waitcnt lgkmcnt(0)
	v_mfma_f32_32x32x16_bf16 v[96:111], v[0:3], v[246:249], v[96:111]
	v_mfma_f32_32x32x16_bf16 v[80:95], v[10:13], v[246:249], v[80:95]
	s_nop 1
	s_cbranch_scc1 .LBB0_974
	s_sub_i32 s24, s93, s5
	s_cmpk_gt_i32 s20, 0x80
	s_cselect_b64 s[4:5], -1, 0
	s_cmpk_lt_i32 s24, 0x201
	s_cselect_b64 s[22:23], -1, 0
	s_and_b64 s[4:5], s[4:5], s[22:23]
	s_cmp_gt_i32 s20, -1
	s_cselect_b64 s[20:21], -1, 0
	s_cmpk_lt_i32 s24, 0x81
	s_cselect_b64 s[22:23], -1, 0
	s_and_b64 s[20:21], s[20:21], s[22:23]
	s_and_b64 s[20:21], s[20:21], exec
	s_cselect_b32 s20, 2, 3
	s_and_b64 s[4:5], s[4:5], exec
	s_cselect_b32 s4, 1, s20
